# weight-copy items: all 32 scale-vector loads of an item issued in one batch (P0 W_gu1, P3 W_in and W_gu2 copies) instead of eight dependent groups
# speedup vs baseline: 1.0033x; 1.0009x over previous
;     ...
;     for (int item = gw; item < nitems; item += ngw) {
;         const int kb = item / nblk, nb = nb0 + item % nblk, k0 = 64 * kb, n0 = 32 * nb;
;         float tv[32];
; #pragma unroll
;         for (int i = 0; i < 32; ++i) { const int kk = 2 * i + (lane >> 5); tv[i] = W[(size_t)(k0 + kk) * N + n0 + (lane & 31)]; }
; #pragma unroll
;         for (int i = 0; i < 32; ++i) { const int kk = 2 * i + (lane >> 5); float v = tv[i]; if (gk) v *= gk[k0 + kk]; scr[kk * 33 + (lane & 31)] = v; }
.LBB0_21:
	s_mul_hi_i32 s6, s34, 0x2e8ba2e9
	s_lshr_b32 s7, s6, 31
	s_ashr_i32 s36, s6, 5
	s_add_i32 s36, s36, s7
	s_mul_i32 s35, s36, 0xffffea00
	s_lshl_b32 s6, s36, 6
	s_add_i32 s10, s14, s35
	v_or_b32_e32 v32, s6, v0
	s_ashr_i32 s11, s10, 31
	v_lshl_add_u64 v[16:17], s[10:11], 2, v[14:15]
	v_or_b32_e32 v5, 2, v32
	v_mad_i64_i32 v[20:21], s[12:13], v5, s33, v[16:17]
	v_or_b32_e32 v5, 4, v32
	v_mad_i64_i32 v[22:23], s[12:13], v5, s33, v[16:17]
	v_or_b32_e32 v5, 6, v32
	v_mad_i64_i32 v[24:25], s[12:13], v5, s33, v[16:17]
	v_or_b32_e32 v5, 8, v32
	v_mad_i64_i32 v[26:27], s[12:13], v5, s33, v[16:17]
	v_or_b32_e32 v5, 10, v32
	v_mad_i64_i32 v[28:29], s[12:13], v5, s33, v[16:17]
	v_or_b32_e32 v5, 12, v32
	v_mad_i64_i32 v[38:39], s[12:13], v5, s33, v[16:17]
	v_or_b32_e32 v5, 14, v32
	v_mad_i64_i32 v[18:19], s[12:13], v32, s33, v[16:17]
	v_mad_i64_i32 v[40:41], s[12:13], v5, s33, v[16:17]
	v_or_b32_e32 v5, 16, v32
	global_load_dword v65, v[18:19], off
	global_load_dword v64, v[20:21], off
	global_load_dword v30, v[22:23], off
	global_load_dword v31, v[24:25], off
	global_load_dword v58, v[26:27], off
	global_load_dword v59, v[28:29], off
	s_nop 0
	global_load_dword v28, v[38:39], off
	global_load_dword v29, v[40:41], off
	v_mad_i64_i32 v[18:19], s[12:13], v5, s33, v[16:17]
	v_or_b32_e32 v5, 18, v32
	v_mad_i64_i32 v[20:21], s[12:13], v5, s33, v[16:17]
	v_or_b32_e32 v5, 20, v32
	v_mad_i64_i32 v[22:23], s[12:13], v5, s33, v[16:17]
	v_or_b32_e32 v5, 22, v32
	v_mad_i64_i32 v[24:25], s[12:13], v5, s33, v[16:17]
	v_or_b32_e32 v5, 24, v32
	v_mad_i64_i32 v[38:39], s[12:13], v5, s33, v[16:17]
	v_or_b32_e32 v5, 26, v32
	v_mad_i64_i32 v[66:67], s[12:13], v5, s33, v[16:17]
	v_or_b32_e32 v5, 28, v32
	v_mad_i64_i32 v[68:69], s[12:13], v5, s33, v[16:17]
	v_or_b32_e32 v5, 30, v32
	v_mad_i64_i32 v[70:71], s[12:13], v5, s33, v[16:17]
	v_or_b32_e32 v5, 32, v32
	global_load_dword v42, v[18:19], off
	global_load_dword v43, v[20:21], off
	global_load_dword v26, v[22:23], off
	global_load_dword v27, v[24:25], off
	global_load_dword v40, v[38:39], off
	global_load_dword v41, v[66:67], off
	s_nop 0
	global_load_dword v24, v[68:69], off
	global_load_dword v25, v[70:71], off
	v_mad_i64_i32 v[18:19], s[12:13], v5, s33, v[16:17]
	v_or_b32_e32 v5, 34, v32
	v_mad_i64_i32 v[20:21], s[12:13], v5, s33, v[16:17]
	v_or_b32_e32 v5, 36, v32
	v_mad_i64_i32 v[22:23], s[12:13], v5, s33, v[16:17]
	v_or_b32_e32 v5, 38, v32
	v_mad_i64_i32 v[66:67], s[12:13], v5, s33, v[16:17]
	v_or_b32_e32 v5, 40, v32
	v_mad_i64_i32 v[68:69], s[12:13], v5, s33, v[16:17]
	v_or_b32_e32 v5, 42, v32
	v_mad_i64_i32 v[70:71], s[12:13], v5, s33, v[16:17]
	v_or_b32_e32 v5, 44, v32
	v_mad_i64_i32 v[72:73], s[12:13], v5, s33, v[16:17]
	v_or_b32_e32 v5, 46, v32
	v_mad_i64_i32 v[74:75], s[12:13], v5, s33, v[16:17]
	v_or_b32_e32 v5, 48, v32
	global_load_dword v38, v[18:19], off
	global_load_dword v39, v[20:21], off
	s_nop 0
	global_load_dword v22, v[22:23], off
	s_nop 0
	global_load_dword v23, v[66:67], off
	global_load_dword v13, v[68:69], off
	global_load_dword v37, v[70:71], off
	global_load_dword v20, v[72:73], off
	global_load_dword v21, v[74:75], off
	v_mad_i64_i32 v[18:19], s[12:13], v5, s33, v[16:17]
	v_or_b32_e32 v5, 50, v32
	v_mad_i64_i32 v[66:67], s[12:13], v5, s33, v[16:17]
	v_or_b32_e32 v5, 52, v32
	v_mad_i64_i32 v[68:69], s[12:13], v5, s33, v[16:17]
	v_or_b32_e32 v5, 54, v32
	v_mad_i64_i32 v[70:71], s[12:13], v5, s33, v[16:17]
	v_or_b32_e32 v5, 56, v32
	v_mad_i64_i32 v[72:73], s[12:13], v5, s33, v[16:17]
	v_or_b32_e32 v5, 58, v32
	v_mad_i64_i32 v[74:75], s[12:13], v5, s33, v[16:17]
	v_or_b32_e32 v5, 60, v32
	v_mad_i64_i32 v[76:77], s[12:13], v5, s33, v[16:17]
	v_or_b32_e32 v5, 62, v32
	v_mad_i64_i32 v[78:79], s[12:13], v5, s33, v[16:17]
	global_load_dword v9, v[18:19], off
	global_load_dword v11, v[66:67], off
	s_nop 0
	global_load_dword v18, v[68:69], off
	global_load_dword v19, v[70:71], off
	global_load_dword v5, v[72:73], off
	global_load_dword v7, v[74:75], off
	global_load_dword v16, v[76:77], off
	global_load_dword v17, v[78:79], off
	s_mov_b32 s38, s72
	s_and_b64 vcc, exec, s[2:3]
	s_cbranch_vccnz .LBB0_44
	v_readlane_b32 s68, v249, 17
	v_ashrrev_i32_e32 v33, 31, v32
	v_readlane_b32 s74, v249, 23
	v_readlane_b32 s75, v249, 24
	s_ashr_i32 s7, s6, 31
	v_lshl_add_u64 v[66:67], s[6:7], 0, v[0:1]
	v_lshl_add_u64 v[32:33], v[32:33], 2, s[74:75]
	v_lshl_add_u64 v[66:67], v[66:67], 2, s[74:75]
	global_load_dword v68, v[32:33], off
	global_load_dword v69, v[66:67], off offset:8
	s_nop 0
	global_load_dword v32, v[66:67], off offset:16
	global_load_dword v33, v[66:67], off offset:24
	global_load_dword v140, v[66:67], off offset:32
	global_load_dword v141, v[66:67], off offset:40
	global_load_dword v142, v[66:67], off offset:48
	global_load_dword v143, v[66:67], off offset:56
	global_load_dword v144, v[66:67], off offset:64
	global_load_dword v145, v[66:67], off offset:72
	global_load_dword v146, v[66:67], off offset:80
	global_load_dword v147, v[66:67], off offset:88
	global_load_dword v148, v[66:67], off offset:96
	global_load_dword v149, v[66:67], off offset:104
	global_load_dword v150, v[66:67], off offset:112
	global_load_dword v151, v[66:67], off offset:120
	global_load_dword v152, v[66:67], off offset:128
	global_load_dword v153, v[66:67], off offset:136
	global_load_dword v154, v[66:67], off offset:144
	global_load_dword v155, v[66:67], off offset:152
	global_load_dword v156, v[66:67], off offset:160
	global_load_dword v157, v[66:67], off offset:168
	global_load_dword v158, v[66:67], off offset:176
	global_load_dword v159, v[66:67], off offset:184
	global_load_dword v160, v[66:67], off offset:192
	global_load_dword v161, v[66:67], off offset:200
	global_load_dword v162, v[66:67], off offset:208
	global_load_dword v163, v[66:67], off offset:216
	global_load_dword v164, v[66:67], off offset:224
	global_load_dword v165, v[66:67], off offset:232
	global_load_dword v166, v[66:67], off offset:240
	global_load_dword v167, v[66:67], off offset:248
	v_add_u32_e32 v66, v46, v34
	v_readlane_b32 s69, v249, 18
	v_readlane_b32 s70, v249, 19
	v_readlane_b32 s71, v249, 20
	v_readlane_b32 s72, v249, 21
	v_readlane_b32 s73, v249, 22
	v_readlane_b32 s76, v249, 25
	v_readlane_b32 s77, v249, 26
	v_readlane_b32 s78, v249, 27
	v_readlane_b32 s79, v249, 28
	v_readlane_b32 s80, v249, 29
	v_readlane_b32 s81, v249, 30
	v_readlane_b32 s82, v249, 31
	v_readlane_b32 s83, v249, 32
	s_waitcnt vmcnt(0)
	v_mul_f32_e32 v67, v65, v68
	s_waitcnt vmcnt(2)
	v_mul_f32_e32 v68, v64, v69
	ds_write_b32 v45, v67
	s_waitcnt vmcnt(0)
	v_pk_mul_f32 v[32:33], v[30:31], v[32:33]
	ds_write_b32 v66, v68
	s_cbranch_execnz .LBB0_24

;     ...
;         for (int i = 0; i < 32; ++i) { const int kk = 2 * i + (lane >> 5); tv[i] = W[(size_t)(k0 + kk) * N + n0 + (lane & 31)]; }
; #pragma unroll
;         for (int i = 0; i < 32; ++i) { const int kk = 2 * i + (lane >> 5); float v = tv[i]; if (gk) v *= gk[k0 + kk]; scr[kk * 33 + (lane & 31)] = v; }
.LBB0_24:
	s_waitcnt vmcnt(0)
	v_add_u32_e32 v30, v46, v35
	s_and_b64 vcc, exec, s[2:3]
	ds_write2_b32 v30, v32, v33 offset1:66
	s_cbranch_vccnz .LBB0_45
	s_ashr_i32 s7, s6, 31
	v_readlane_b32 s68, v249, 17
	s_waitcnt vmcnt(0)
	v_lshl_add_u64 v[30:31], s[6:7], 0, v[0:1]
	v_readlane_b32 s74, v249, 23
	v_readlane_b32 s75, v249, 24
	v_add_u32_e32 v66, v46, v36
	s_nop 0
	v_lshl_add_u64 v[30:31], v[30:31], 2, s[74:75]
	v_readlane_b32 s69, v249, 18
	v_readlane_b32 s70, v249, 19
	v_readlane_b32 s71, v249, 20
	v_readlane_b32 s72, v249, 21
	v_readlane_b32 s73, v249, 22
	v_readlane_b32 s76, v249, 25
	v_readlane_b32 s77, v249, 26
	v_readlane_b32 s78, v249, 27
	v_readlane_b32 s79, v249, 28
	v_readlane_b32 s80, v249, 29
	v_readlane_b32 s81, v249, 30
	v_readlane_b32 s82, v249, 31
	v_readlane_b32 s83, v249, 32
	s_waitcnt vmcnt(0)
	v_mul_f32_e32 v64, v58, v140
	s_waitcnt vmcnt(2)
	v_mul_f32_e32 v65, v59, v141
	ds_write2_b32 v66, v64, v65 offset1:66
	s_waitcnt vmcnt(0)
	v_pk_mul_f32 v[30:31], v[28:29], v[142:143]
	s_cbranch_execnz .LBB0_27

;     ...
;         for (int i = 0; i < 32; ++i) { const int kk = 2 * i + (lane >> 5); tv[i] = W[(size_t)(k0 + kk) * N + n0 + (lane & 31)]; }
; #pragma unroll
;         for (int i = 0; i < 32; ++i) { const int kk = 2 * i + (lane >> 5); float v = tv[i]; if (gk) v *= gk[k0 + kk]; scr[kk * 33 + (lane & 31)] = v; }
.LBB0_27:
	s_waitcnt vmcnt(0)
	v_add_u32_e32 v28, v46, v47
	s_and_b64 vcc, exec, s[2:3]
	ds_write2_b32 v28, v30, v31 offset1:66
	s_cbranch_vccnz .LBB0_46
	s_ashr_i32 s7, s6, 31
	v_readlane_b32 s68, v249, 17
	s_waitcnt vmcnt(0)
	v_lshl_add_u64 v[28:29], s[6:7], 0, v[0:1]
	v_readlane_b32 s74, v249, 23
	v_readlane_b32 s75, v249, 24
	v_add_u32_e32 v58, v46, v48
	s_nop 0
	v_lshl_add_u64 v[28:29], v[28:29], 2, s[74:75]
	v_readlane_b32 s69, v249, 18
	v_readlane_b32 s70, v249, 19
	v_readlane_b32 s71, v249, 20
	v_readlane_b32 s72, v249, 21
	v_readlane_b32 s73, v249, 22
	v_readlane_b32 s76, v249, 25
	v_readlane_b32 s77, v249, 26
	v_readlane_b32 s78, v249, 27
	v_readlane_b32 s79, v249, 28
	v_readlane_b32 s80, v249, 29
	v_readlane_b32 s81, v249, 30
	v_readlane_b32 s82, v249, 31
	v_readlane_b32 s83, v249, 32
	s_waitcnt vmcnt(0)
	v_mul_f32_e32 v32, v42, v144
	s_waitcnt vmcnt(2)
	v_mul_f32_e32 v33, v43, v145
	ds_write2_b32 v58, v32, v33 offset1:66
	s_waitcnt vmcnt(0)
	v_pk_mul_f32 v[28:29], v[26:27], v[146:147]
	s_cbranch_execnz .LBB0_30

;     ...
;         for (int i = 0; i < 32; ++i) { const int kk = 2 * i + (lane >> 5); tv[i] = W[(size_t)(k0 + kk) * N + n0 + (lane & 31)]; }
; #pragma unroll
;         for (int i = 0; i < 32; ++i) { const int kk = 2 * i + (lane >> 5); float v = tv[i]; if (gk) v *= gk[k0 + kk]; scr[kk * 33 + (lane & 31)] = v; }
.LBB0_30:
	s_waitcnt vmcnt(0)
	v_add_u32_e32 v26, v46, v49
	s_and_b64 vcc, exec, s[2:3]
	ds_write2_b32 v26, v28, v29 offset1:66
	s_cbranch_vccnz .LBB0_47
	s_ashr_i32 s7, s6, 31
	v_readlane_b32 s68, v249, 17
	s_waitcnt vmcnt(0)
	v_lshl_add_u64 v[26:27], s[6:7], 0, v[0:1]
	v_readlane_b32 s74, v249, 23
	v_readlane_b32 s75, v249, 24
	v_add_u32_e32 v32, v46, v50
	s_nop 0
	v_lshl_add_u64 v[26:27], v[26:27], 2, s[74:75]
	v_readlane_b32 s69, v249, 18
	v_readlane_b32 s70, v249, 19
	v_readlane_b32 s71, v249, 20
	v_readlane_b32 s72, v249, 21
	v_readlane_b32 s73, v249, 22
	v_readlane_b32 s76, v249, 25
	v_readlane_b32 s77, v249, 26
	v_readlane_b32 s78, v249, 27
	v_readlane_b32 s79, v249, 28
	v_readlane_b32 s80, v249, 29
	v_readlane_b32 s81, v249, 30
	v_readlane_b32 s82, v249, 31
	v_readlane_b32 s83, v249, 32
	s_waitcnt vmcnt(0)
	v_mul_f32_e32 v30, v40, v148
	s_waitcnt vmcnt(2)
	v_mul_f32_e32 v31, v41, v149
	ds_write2_b32 v32, v30, v31 offset1:66
	s_waitcnt vmcnt(0)
	v_pk_mul_f32 v[26:27], v[24:25], v[150:151]
	s_cbranch_execnz .LBB0_33

;     ...
;         for (int i = 0; i < 32; ++i) { const int kk = 2 * i + (lane >> 5); tv[i] = W[(size_t)(k0 + kk) * N + n0 + (lane & 31)]; }
; #pragma unroll
;         for (int i = 0; i < 32; ++i) { const int kk = 2 * i + (lane >> 5); float v = tv[i]; if (gk) v *= gk[k0 + kk]; scr[kk * 33 + (lane & 31)] = v; }
.LBB0_33:
	s_waitcnt vmcnt(0)
	v_add_u32_e32 v24, v46, v51
	s_and_b64 vcc, exec, s[2:3]
	ds_write2_b32 v24, v26, v27 offset1:66
	s_cbranch_vccnz .LBB0_48
	s_ashr_i32 s7, s6, 31
	v_readlane_b32 s68, v249, 17
	s_waitcnt vmcnt(0)
	v_lshl_add_u64 v[24:25], s[6:7], 0, v[0:1]
	v_readlane_b32 s74, v249, 23
	v_readlane_b32 s75, v249, 24
	v_add_u32_e32 v30, v46, v52
	s_nop 0
	v_lshl_add_u64 v[24:25], v[24:25], 2, s[74:75]
	v_readlane_b32 s69, v249, 18
	v_readlane_b32 s70, v249, 19
	v_readlane_b32 s71, v249, 20
	v_readlane_b32 s72, v249, 21
	v_readlane_b32 s73, v249, 22
	v_readlane_b32 s76, v249, 25
	v_readlane_b32 s77, v249, 26
	v_readlane_b32 s78, v249, 27
	v_readlane_b32 s79, v249, 28
	v_readlane_b32 s80, v249, 29
	v_readlane_b32 s81, v249, 30
	v_readlane_b32 s82, v249, 31
	v_readlane_b32 s83, v249, 32
	s_waitcnt vmcnt(0)
	v_mul_f32_e32 v28, v38, v152
	s_waitcnt vmcnt(2)
	v_mul_f32_e32 v29, v39, v153
	ds_write2_b32 v30, v28, v29 offset1:66
	s_waitcnt vmcnt(0)
	v_pk_mul_f32 v[24:25], v[22:23], v[154:155]
	s_cbranch_execnz .LBB0_36

;     ...
;         for (int i = 0; i < 32; ++i) { const int kk = 2 * i + (lane >> 5); tv[i] = W[(size_t)(k0 + kk) * N + n0 + (lane & 31)]; }
; #pragma unroll
;         for (int i = 0; i < 32; ++i) { const int kk = 2 * i + (lane >> 5); float v = tv[i]; if (gk) v *= gk[k0 + kk]; scr[kk * 33 + (lane & 31)] = v; }
.LBB0_36:
	s_waitcnt vmcnt(0)
	v_add_u32_e32 v22, v46, v53
	s_and_b64 vcc, exec, s[2:3]
	ds_write2_b32 v22, v24, v25 offset1:66
	s_cbranch_vccnz .LBB0_49
	s_ashr_i32 s7, s6, 31
	v_readlane_b32 s68, v249, 17
	s_waitcnt vmcnt(0)
	v_lshl_add_u64 v[22:23], s[6:7], 0, v[0:1]
	v_readlane_b32 s74, v249, 23
	v_readlane_b32 s75, v249, 24
	v_add_u32_e32 v28, v46, v54
	s_nop 0
	v_lshl_add_u64 v[22:23], v[22:23], 2, s[74:75]
	v_readlane_b32 s69, v249, 18
	v_readlane_b32 s70, v249, 19
	v_readlane_b32 s71, v249, 20
	v_readlane_b32 s72, v249, 21
	v_readlane_b32 s73, v249, 22
	v_readlane_b32 s76, v249, 25
	v_readlane_b32 s77, v249, 26
	v_readlane_b32 s78, v249, 27
	v_readlane_b32 s79, v249, 28
	v_readlane_b32 s80, v249, 29
	v_readlane_b32 s81, v249, 30
	v_readlane_b32 s82, v249, 31
	v_readlane_b32 s83, v249, 32
	s_waitcnt vmcnt(0)
	v_mul_f32_e32 v26, v13, v156
	s_waitcnt vmcnt(2)
	v_mul_f32_e32 v27, v37, v157
	ds_write2_b32 v28, v26, v27 offset1:66
	s_waitcnt vmcnt(0)
	v_pk_mul_f32 v[22:23], v[20:21], v[158:159]
	s_cbranch_execnz .LBB0_39

;     ...
;         for (int i = 0; i < 32; ++i) { const int kk = 2 * i + (lane >> 5); tv[i] = W[(size_t)(k0 + kk) * N + n0 + (lane & 31)]; }
; #pragma unroll
;         for (int i = 0; i < 32; ++i) { const int kk = 2 * i + (lane >> 5); float v = tv[i]; if (gk) v *= gk[k0 + kk]; scr[kk * 33 + (lane & 31)] = v; }
.LBB0_39:
	s_waitcnt vmcnt(0)
	v_add_u32_e32 v13, v46, v55
	s_and_b64 vcc, exec, s[2:3]
	ds_write2_b32 v13, v22, v23 offset1:66
	s_cbranch_vccnz .LBB0_50
	s_ashr_i32 s7, s6, 31
	v_readlane_b32 s68, v249, 17
	s_waitcnt vmcnt(0)
	v_lshl_add_u64 v[20:21], s[6:7], 0, v[0:1]
	v_readlane_b32 s74, v249, 23
	v_readlane_b32 s75, v249, 24
	v_add_u32_e32 v25, v46, v56
	s_nop 0
	v_lshl_add_u64 v[20:21], v[20:21], 2, s[74:75]
	v_readlane_b32 s69, v249, 18
	v_readlane_b32 s70, v249, 19
	v_readlane_b32 s71, v249, 20
	v_readlane_b32 s72, v249, 21
	v_readlane_b32 s73, v249, 22
	v_readlane_b32 s76, v249, 25
	v_readlane_b32 s77, v249, 26
	v_readlane_b32 s78, v249, 27
	v_readlane_b32 s79, v249, 28
	v_readlane_b32 s80, v249, 29
	v_readlane_b32 s81, v249, 30
	v_readlane_b32 s82, v249, 31
	v_readlane_b32 s83, v249, 32
	s_waitcnt vmcnt(0)
	v_mul_f32_e32 v13, v9, v160
	s_waitcnt vmcnt(2)
	v_mul_f32_e32 v24, v11, v161
	ds_write2_b32 v25, v13, v24 offset1:66
	s_waitcnt vmcnt(0)
	v_pk_mul_f32 v[20:21], v[18:19], v[162:163]
	s_cbranch_execnz .LBB0_42

;     ...
;         for (int i = 0; i < 32; ++i) { const int kk = 2 * i + (lane >> 5); tv[i] = W[(size_t)(k0 + kk) * N + n0 + (lane & 31)]; }
; #pragma unroll
;         for (int i = 0; i < 32; ++i) { const int kk = 2 * i + (lane >> 5); float v = tv[i]; if (gk) v *= gk[k0 + kk]; scr[kk * 33 + (lane & 31)] = v; }
.LBB0_42:
	s_waitcnt vmcnt(0)
	v_add_u32_e32 v9, v46, v57
	s_and_b64 vcc, exec, s[2:3]
	ds_write2_b32 v9, v20, v21 offset1:66
	s_cbranch_vccnz .LBB0_51
	s_ashr_i32 s7, s6, 31
	v_readlane_b32 s68, v249, 17
	s_waitcnt vmcnt(0)
	v_lshl_add_u64 v[18:19], s[6:7], 0, v[0:1]
	v_readlane_b32 s74, v249, 23
	v_readlane_b32 s75, v249, 24
	v_readlane_b32 s69, v249, 18
	s_nop 0
	v_lshl_add_u64 v[18:19], v[18:19], 2, s[74:75]
	v_readlane_b32 s70, v249, 19
	v_readlane_b32 s71, v249, 20
	v_readlane_b32 s72, v249, 21
	v_readlane_b32 s73, v249, 22
	v_readlane_b32 s76, v249, 25
	v_readlane_b32 s77, v249, 26
	v_readlane_b32 s78, v249, 27
	v_readlane_b32 s79, v249, 28
	v_readlane_b32 s80, v249, 29
	v_readlane_b32 s81, v249, 30
	v_readlane_b32 s82, v249, 31
	v_readlane_b32 s83, v249, 32
	s_waitcnt vmcnt(0)
	v_mul_f32_e32 v11, v5, v164
	s_waitcnt vmcnt(2)
	v_mul_f32_e32 v13, v7, v165
	ds_write2_b32 v9, v11, v13 offset0:132 offset1:198
	s_waitcnt vmcnt(0)
	v_pk_mul_f32 v[18:19], v[16:17], v[166:167]
	s_mov_b32 s72, s38
	s_cbranch_execnz .LBB0_20
	s_branch .LBB0_52

;     ...
;     for (int item = gw; item < nitems; item += ngw) {
;         const int kb = item / nblk, nb = nb0 + item % nblk, k0 = 64 * kb, n0 = 32 * nb;
;         float tv[32];
; #pragma unroll
;         for (int i = 0; i < 32; ++i) { const int kk = 2 * i + (lane >> 5); tv[i] = W[(size_t)(k0 + kk) * N + n0 + (lane & 31)]; }
; #pragma unroll
;         for (int i = 0; i < 32; ++i) { const int kk = 2 * i + (lane >> 5); float v = tv[i]; if (gk) v *= gk[k0 + kk]; scr[kk * 33 + (lane & 31)] = v; }
; __global__ void __launch_bounds__(512, 2) fwd_mega(Args args) {
;     ...
;             transpose_mat(args.in[7], 1024, 5280, args.in[6], 2, wIN, wGT, scr, gw2, ngw2, lane, 69, 165);
.LBB0_1027:
	s_mul_hi_i32 s0, s52, 0x2aaaaaab
	s_lshr_b32 s2, s0, 31
	s_ashr_i32 s37, s0, 4
	s_add_i32 s53, s37, s2
	s_mul_i32 s0, s53, 0xfffff400
	s_add_i32 s0, s33, s0
	s_lshl_b32 s6, s53, 6
	s_add_i32 s8, s0, 0x8a0
	v_or_b32_e32 v32, s6, v0
	s_ashr_i32 s9, s8, 31
	v_lshl_add_u64 v[16:17], s[8:9], 2, v[14:15]
	v_or_b32_e32 v5, 2, v32
	v_mad_i64_i32 v[20:21], s[2:3], v5, s35, v[16:17]
	v_or_b32_e32 v5, 4, v32
	v_mad_i64_i32 v[22:23], s[2:3], v5, s35, v[16:17]
	v_or_b32_e32 v5, 6, v32
	v_mad_i64_i32 v[24:25], s[2:3], v5, s35, v[16:17]
	v_or_b32_e32 v5, 8, v32
	v_mad_i64_i32 v[26:27], s[2:3], v5, s35, v[16:17]
	v_or_b32_e32 v5, 10, v32
	v_mad_i64_i32 v[28:29], s[2:3], v5, s35, v[16:17]
	v_or_b32_e32 v5, 12, v32
	v_mad_i64_i32 v[52:53], s[2:3], v5, s35, v[16:17]
	v_or_b32_e32 v5, 14, v32
	v_mad_i64_i32 v[18:19], s[2:3], v32, s35, v[16:17]
	v_mad_i64_i32 v[54:55], s[2:3], v5, s35, v[16:17]
	v_or_b32_e32 v5, 16, v32
	global_load_dword v62, v[18:19], off
	global_load_dword v61, v[20:21], off
	global_load_dword v30, v[22:23], off
	global_load_dword v31, v[24:25], off
	global_load_dword v59, v[26:27], off
	global_load_dword v60, v[28:29], off
	s_nop 0
	global_load_dword v28, v[52:53], off
	global_load_dword v29, v[54:55], off
	v_mad_i64_i32 v[18:19], s[2:3], v5, s35, v[16:17]
	v_or_b32_e32 v5, 18, v32
	v_mad_i64_i32 v[20:21], s[2:3], v5, s35, v[16:17]
	v_or_b32_e32 v5, 20, v32
	v_mad_i64_i32 v[22:23], s[2:3], v5, s35, v[16:17]
	v_or_b32_e32 v5, 22, v32
	v_mad_i64_i32 v[24:25], s[2:3], v5, s35, v[16:17]
	v_or_b32_e32 v5, 24, v32
	v_mad_i64_i32 v[52:53], s[2:3], v5, s35, v[16:17]
	v_or_b32_e32 v5, 26, v32
	v_mad_i64_i32 v[64:65], s[2:3], v5, s35, v[16:17]
	v_or_b32_e32 v5, 28, v32
	v_mad_i64_i32 v[66:67], s[2:3], v5, s35, v[16:17]
	v_or_b32_e32 v5, 30, v32
	v_mad_i64_i32 v[68:69], s[2:3], v5, s35, v[16:17]
	v_or_b32_e32 v5, 32, v32
	global_load_dword v57, v[18:19], off
	global_load_dword v58, v[20:21], off
	global_load_dword v26, v[22:23], off
	global_load_dword v27, v[24:25], off
	global_load_dword v55, v[52:53], off
	global_load_dword v56, v[64:65], off
	s_nop 0
	global_load_dword v24, v[66:67], off
	global_load_dword v25, v[68:69], off
	v_mad_i64_i32 v[18:19], s[2:3], v5, s35, v[16:17]
	v_or_b32_e32 v5, 34, v32
	v_mad_i64_i32 v[20:21], s[2:3], v5, s35, v[16:17]
	v_or_b32_e32 v5, 36, v32
	v_mad_i64_i32 v[22:23], s[2:3], v5, s35, v[16:17]
	v_or_b32_e32 v5, 38, v32
	v_mad_i64_i32 v[64:65], s[2:3], v5, s35, v[16:17]
	v_or_b32_e32 v5, 40, v32
	v_mad_i64_i32 v[66:67], s[2:3], v5, s35, v[16:17]
	v_or_b32_e32 v5, 42, v32
	v_mad_i64_i32 v[68:69], s[2:3], v5, s35, v[16:17]
	v_or_b32_e32 v5, 44, v32
	v_mad_i64_i32 v[70:71], s[2:3], v5, s35, v[16:17]
	v_or_b32_e32 v5, 46, v32
	v_mad_i64_i32 v[72:73], s[2:3], v5, s35, v[16:17]
	v_or_b32_e32 v5, 48, v32
	global_load_dword v53, v[18:19], off
	global_load_dword v54, v[20:21], off
	s_nop 0
	global_load_dword v22, v[22:23], off
	s_nop 0
	global_load_dword v23, v[64:65], off
	global_load_dword v13, v[66:67], off
	global_load_dword v52, v[68:69], off
	global_load_dword v20, v[70:71], off
	global_load_dword v21, v[72:73], off
	v_mad_i64_i32 v[18:19], s[2:3], v5, s35, v[16:17]
	v_or_b32_e32 v5, 50, v32
	v_mad_i64_i32 v[64:65], s[2:3], v5, s35, v[16:17]
	v_or_b32_e32 v5, 52, v32
	v_mad_i64_i32 v[66:67], s[2:3], v5, s35, v[16:17]
	v_or_b32_e32 v5, 54, v32
	v_mad_i64_i32 v[68:69], s[2:3], v5, s35, v[16:17]
	v_or_b32_e32 v5, 56, v32
	v_mad_i64_i32 v[70:71], s[2:3], v5, s35, v[16:17]
	v_or_b32_e32 v5, 58, v32
	v_mad_i64_i32 v[72:73], s[2:3], v5, s35, v[16:17]
	v_or_b32_e32 v5, 60, v32
	v_mad_i64_i32 v[74:75], s[2:3], v5, s35, v[16:17]
	v_or_b32_e32 v5, 62, v32
	v_mad_i64_i32 v[76:77], s[2:3], v5, s35, v[16:17]
	global_load_dword v9, v[18:19], off
	global_load_dword v11, v[64:65], off
	s_nop 0
	global_load_dword v18, v[66:67], off
	global_load_dword v19, v[68:69], off
	global_load_dword v5, v[70:71], off
	global_load_dword v7, v[72:73], off
	global_load_dword v16, v[74:75], off
	global_load_dword v17, v[76:77], off
	s_and_b64 vcc, exec, s[4:5]
	s_cbranch_vccz .LBB0_1063
	v_readlane_b32 s36, v249, 17
	v_ashrrev_i32_e32 v33, 31, v32
	v_readlane_b32 s48, v249, 29
	v_readlane_b32 s49, v249, 30
	s_ashr_i32 s7, s6, 31
	v_lshl_add_u64 v[64:65], s[6:7], 0, v[0:1]
	v_lshl_add_u64 v[32:33], v[32:33], 2, s[48:49]
	v_lshl_add_u64 v[64:65], v[64:65], 2, s[48:49]
	global_load_dword v63, v[32:33], off
	global_load_dword v66, v[64:65], off offset:8
	s_nop 0
	global_load_dword v32, v[64:65], off offset:16
	global_load_dword v33, v[64:65], off offset:24
	global_load_dword v140, v[64:65], off offset:32
	global_load_dword v141, v[64:65], off offset:40
	global_load_dword v142, v[64:65], off offset:48
	global_load_dword v143, v[64:65], off offset:56
	global_load_dword v144, v[64:65], off offset:64
	global_load_dword v145, v[64:65], off offset:72
	global_load_dword v146, v[64:65], off offset:80
	global_load_dword v147, v[64:65], off offset:88
	global_load_dword v148, v[64:65], off offset:96
	global_load_dword v149, v[64:65], off offset:104
	global_load_dword v150, v[64:65], off offset:112
	global_load_dword v151, v[64:65], off offset:120
	global_load_dword v152, v[64:65], off offset:128
	global_load_dword v153, v[64:65], off offset:136
	global_load_dword v154, v[64:65], off offset:144
	global_load_dword v155, v[64:65], off offset:152
	global_load_dword v156, v[64:65], off offset:160
	global_load_dword v157, v[64:65], off offset:168
	global_load_dword v158, v[64:65], off offset:176
	global_load_dword v159, v[64:65], off offset:184
	global_load_dword v160, v[64:65], off offset:192
	global_load_dword v161, v[64:65], off offset:200
	global_load_dword v162, v[64:65], off offset:208
	global_load_dword v163, v[64:65], off offset:216
	global_load_dword v164, v[64:65], off offset:224
	global_load_dword v165, v[64:65], off offset:232
	global_load_dword v166, v[64:65], off offset:240
	global_load_dword v167, v[64:65], off offset:248
	v_add_u32_e32 v64, v37, v46
	v_readlane_b32 s37, v249, 18
	v_readlane_b32 s38, v249, 19
	v_readlane_b32 s39, v249, 20
	v_readlane_b32 s40, v249, 21
	v_readlane_b32 s41, v249, 22
	v_readlane_b32 s42, v249, 23
	v_readlane_b32 s43, v249, 24
	v_readlane_b32 s44, v249, 25
	v_readlane_b32 s45, v249, 26
	v_readlane_b32 s46, v249, 27
	v_readlane_b32 s47, v249, 28
	v_readlane_b32 s50, v249, 31
	v_readlane_b32 s51, v249, 32
	s_waitcnt vmcnt(0)
	v_mul_f32_e32 v63, v62, v63
	v_mul_f32_e32 v65, v61, v66
	ds_write_b32 v35, v63
	v_pk_mul_f32 v[32:33], v[30:31], v[32:33]
	ds_write_b32 v64, v65
	s_cbranch_execnz .LBB0_1030

;     ...
;         for (int i = 0; i < 32; ++i) { const int kk = 2 * i + (lane >> 5); tv[i] = W[(size_t)(k0 + kk) * N + n0 + (lane & 31)]; }
; #pragma unroll
;         for (int i = 0; i < 32; ++i) { const int kk = 2 * i + (lane >> 5); float v = tv[i]; if (gk) v *= gk[k0 + kk]; scr[kk * 33 + (lane & 31)] = v; }
.LBB0_1030:
	s_waitcnt vmcnt(0)
	v_cndmask_b32_e64 v31, 0, 1, s[4:5]
	v_add_u32_e32 v30, v37, v47
	v_cmp_ne_u32_e64 s[2:3], 1, v31
	s_andn2_b64 vcc, exec, s[4:5]
	ds_write2_b32 v30, v32, v33 offset1:66
	s_cbranch_vccnz .LBB0_1064
	s_ashr_i32 s7, s6, 31
	v_readlane_b32 s36, v249, 17
	v_lshl_add_u64 v[30:31], s[6:7], 0, v[0:1]
	v_readlane_b32 s48, v249, 29
	v_readlane_b32 s49, v249, 30
	v_add_u32_e32 v63, v37, v48
	s_nop 0
	v_lshl_add_u64 v[30:31], v[30:31], 2, s[48:49]
	v_readlane_b32 s37, v249, 18
	v_readlane_b32 s38, v249, 19
	v_readlane_b32 s39, v249, 20
	v_readlane_b32 s40, v249, 21
	v_readlane_b32 s41, v249, 22
	v_readlane_b32 s42, v249, 23
	v_readlane_b32 s43, v249, 24
	v_readlane_b32 s44, v249, 25
	v_readlane_b32 s45, v249, 26
	v_readlane_b32 s46, v249, 27
	v_readlane_b32 s47, v249, 28
	v_readlane_b32 s50, v249, 31
	v_readlane_b32 s51, v249, 32
	s_waitcnt vmcnt(0)
	v_mul_f32_e32 v61, v59, v140
	s_waitcnt vmcnt(2)
	v_mul_f32_e32 v62, v60, v141
	ds_write2_b32 v63, v61, v62 offset1:66
	s_waitcnt vmcnt(0)
	v_pk_mul_f32 v[30:31], v[28:29], v[142:143]
	s_cbranch_execnz .LBB0_1033

;     ...
;         for (int i = 0; i < 32; ++i) { const int kk = 2 * i + (lane >> 5); tv[i] = W[(size_t)(k0 + kk) * N + n0 + (lane & 31)]; }
; #pragma unroll
;         for (int i = 0; i < 32; ++i) { const int kk = 2 * i + (lane >> 5); float v = tv[i]; if (gk) v *= gk[k0 + kk]; scr[kk * 33 + (lane & 31)] = v; }
.LBB0_1033:
	v_add_u32_e32 v28, v37, v38
	s_and_b64 vcc, exec, s[2:3]
	ds_write2_b32 v28, v30, v31 offset1:66
	s_cbranch_vccnz .LBB0_1065
	s_ashr_i32 s7, s6, 31
	v_readlane_b32 s36, v249, 17
	v_lshl_add_u64 v[28:29], s[6:7], 0, v[0:1]
	v_readlane_b32 s48, v249, 29
	v_readlane_b32 s49, v249, 30
	v_add_u32_e32 v59, v37, v39
	s_nop 0
	v_lshl_add_u64 v[28:29], v[28:29], 2, s[48:49]
	v_readlane_b32 s37, v249, 18
	v_readlane_b32 s38, v249, 19
	v_readlane_b32 s39, v249, 20
	v_readlane_b32 s40, v249, 21
	v_readlane_b32 s41, v249, 22
	v_readlane_b32 s42, v249, 23
	v_readlane_b32 s43, v249, 24
	v_readlane_b32 s44, v249, 25
	v_readlane_b32 s45, v249, 26
	v_readlane_b32 s46, v249, 27
	v_readlane_b32 s47, v249, 28
	v_readlane_b32 s50, v249, 31
	v_readlane_b32 s51, v249, 32
	s_waitcnt vmcnt(0)
	v_mul_f32_e32 v32, v57, v144
	s_waitcnt vmcnt(2)
	v_mul_f32_e32 v33, v58, v145
	ds_write2_b32 v59, v32, v33 offset1:66
	s_waitcnt vmcnt(0)
	v_pk_mul_f32 v[28:29], v[26:27], v[146:147]
	s_cbranch_execnz .LBB0_1036

;     ...
;         for (int i = 0; i < 32; ++i) { const int kk = 2 * i + (lane >> 5); tv[i] = W[(size_t)(k0 + kk) * N + n0 + (lane & 31)]; }
; #pragma unroll
;         for (int i = 0; i < 32; ++i) { const int kk = 2 * i + (lane >> 5); float v = tv[i]; if (gk) v *= gk[k0 + kk]; scr[kk * 33 + (lane & 31)] = v; }
.LBB0_1036:
	v_add_u32_e32 v26, v37, v40
	s_and_b64 vcc, exec, s[2:3]
	ds_write2_b32 v26, v28, v29 offset1:66
	s_cbranch_vccnz .LBB0_1066
	s_ashr_i32 s7, s6, 31
	v_readlane_b32 s36, v249, 17
	v_lshl_add_u64 v[26:27], s[6:7], 0, v[0:1]
	v_readlane_b32 s48, v249, 29
	v_readlane_b32 s49, v249, 30
	v_add_u32_e32 v32, v37, v41
	s_nop 0
	v_lshl_add_u64 v[26:27], v[26:27], 2, s[48:49]
	v_readlane_b32 s37, v249, 18
	v_readlane_b32 s38, v249, 19
	v_readlane_b32 s39, v249, 20
	v_readlane_b32 s40, v249, 21
	v_readlane_b32 s41, v249, 22
	v_readlane_b32 s42, v249, 23
	v_readlane_b32 s43, v249, 24
	v_readlane_b32 s44, v249, 25
	v_readlane_b32 s45, v249, 26
	v_readlane_b32 s46, v249, 27
	v_readlane_b32 s47, v249, 28
	v_readlane_b32 s50, v249, 31
	v_readlane_b32 s51, v249, 32
	s_waitcnt vmcnt(0)
	v_mul_f32_e32 v30, v55, v148
	s_waitcnt vmcnt(2)
	v_mul_f32_e32 v31, v56, v149
	ds_write2_b32 v32, v30, v31 offset1:66
	s_waitcnt vmcnt(0)
	v_pk_mul_f32 v[26:27], v[24:25], v[150:151]
	s_cbranch_execnz .LBB0_1039

;     ...
;         for (int i = 0; i < 32; ++i) { const int kk = 2 * i + (lane >> 5); tv[i] = W[(size_t)(k0 + kk) * N + n0 + (lane & 31)]; }
; #pragma unroll
;         for (int i = 0; i < 32; ++i) { const int kk = 2 * i + (lane >> 5); float v = tv[i]; if (gk) v *= gk[k0 + kk]; scr[kk * 33 + (lane & 31)] = v; }
.LBB0_1039:
	v_add_u32_e32 v24, v37, v42
	s_and_b64 vcc, exec, s[2:3]
	ds_write2_b32 v24, v26, v27 offset1:66
	s_cbranch_vccnz .LBB0_1067
	s_ashr_i32 s7, s6, 31
	v_readlane_b32 s36, v249, 17
	v_lshl_add_u64 v[24:25], s[6:7], 0, v[0:1]
	v_readlane_b32 s48, v249, 29
	v_readlane_b32 s49, v249, 30
	v_add_u32_e32 v30, v37, v43
	s_nop 0
	v_lshl_add_u64 v[24:25], v[24:25], 2, s[48:49]
	v_readlane_b32 s37, v249, 18
	v_readlane_b32 s38, v249, 19
	v_readlane_b32 s39, v249, 20
	v_readlane_b32 s40, v249, 21
	v_readlane_b32 s41, v249, 22
	v_readlane_b32 s42, v249, 23
	v_readlane_b32 s43, v249, 24
	v_readlane_b32 s44, v249, 25
	v_readlane_b32 s45, v249, 26
	v_readlane_b32 s46, v249, 27
	v_readlane_b32 s47, v249, 28
	v_readlane_b32 s50, v249, 31
	v_readlane_b32 s51, v249, 32
	s_waitcnt vmcnt(0)
	v_mul_f32_e32 v28, v53, v152
	s_waitcnt vmcnt(2)
	v_mul_f32_e32 v29, v54, v153
	ds_write2_b32 v30, v28, v29 offset1:66
	s_waitcnt vmcnt(0)
	v_pk_mul_f32 v[24:25], v[22:23], v[154:155]
	s_cbranch_execnz .LBB0_1042

;     ...
;         for (int i = 0; i < 32; ++i) { const int kk = 2 * i + (lane >> 5); tv[i] = W[(size_t)(k0 + kk) * N + n0 + (lane & 31)]; }
; #pragma unroll
;         for (int i = 0; i < 32; ++i) { const int kk = 2 * i + (lane >> 5); float v = tv[i]; if (gk) v *= gk[k0 + kk]; scr[kk * 33 + (lane & 31)] = v; }
.LBB0_1042:
	v_add_u32_e32 v22, v37, v44
	s_and_b64 vcc, exec, s[2:3]
	ds_write2_b32 v22, v24, v25 offset1:66
	s_cbranch_vccnz .LBB0_1068
	s_ashr_i32 s7, s6, 31
	v_readlane_b32 s36, v249, 17
	v_lshl_add_u64 v[22:23], s[6:7], 0, v[0:1]
	v_readlane_b32 s48, v249, 29
	v_readlane_b32 s49, v249, 30
	v_add_u32_e32 v28, v37, v45
	s_nop 0
	v_lshl_add_u64 v[22:23], v[22:23], 2, s[48:49]
	v_readlane_b32 s37, v249, 18
	v_readlane_b32 s38, v249, 19
	v_readlane_b32 s39, v249, 20
	v_readlane_b32 s40, v249, 21
	v_readlane_b32 s41, v249, 22
	v_readlane_b32 s42, v249, 23
	v_readlane_b32 s43, v249, 24
	v_readlane_b32 s44, v249, 25
	v_readlane_b32 s45, v249, 26
	v_readlane_b32 s46, v249, 27
	v_readlane_b32 s47, v249, 28
	v_readlane_b32 s50, v249, 31
	v_readlane_b32 s51, v249, 32
	s_waitcnt vmcnt(0)
	v_mul_f32_e32 v26, v13, v156
	s_waitcnt vmcnt(2)
	v_mul_f32_e32 v27, v52, v157
	ds_write2_b32 v28, v26, v27 offset1:66
	s_waitcnt vmcnt(0)
	v_pk_mul_f32 v[22:23], v[20:21], v[158:159]
	s_cbranch_execnz .LBB0_1045

;     ...
;         for (int i = 0; i < 32; ++i) { const int kk = 2 * i + (lane >> 5); tv[i] = W[(size_t)(k0 + kk) * N + n0 + (lane & 31)]; }
; #pragma unroll
;         for (int i = 0; i < 32; ++i) { const int kk = 2 * i + (lane >> 5); float v = tv[i]; if (gk) v *= gk[k0 + kk]; scr[kk * 33 + (lane & 31)] = v; }
.LBB0_1045:
	v_add_u32_e32 v13, v37, v45
	ds_write2_b32 v13, v22, v23 offset0:132 offset1:198
	s_and_b64 vcc, exec, s[2:3]
	v_add_u32_e32 v22, 0x400, v13
	s_cbranch_vccnz .LBB0_1069
	s_ashr_i32 s7, s6, 31
	v_readlane_b32 s36, v249, 17
	v_lshl_add_u64 v[20:21], s[6:7], 0, v[0:1]
	v_readlane_b32 s48, v249, 29
	v_readlane_b32 s49, v249, 30
	v_readlane_b32 s37, v249, 18
	s_nop 0
	v_lshl_add_u64 v[20:21], v[20:21], 2, s[48:49]
	v_readlane_b32 s38, v249, 19
	v_readlane_b32 s39, v249, 20
	v_readlane_b32 s40, v249, 21
	v_readlane_b32 s41, v249, 22
	v_readlane_b32 s42, v249, 23
	v_readlane_b32 s43, v249, 24
	v_readlane_b32 s44, v249, 25
	v_readlane_b32 s45, v249, 26
	v_readlane_b32 s46, v249, 27
	v_readlane_b32 s47, v249, 28
	v_readlane_b32 s50, v249, 31
	v_readlane_b32 s51, v249, 32
	s_waitcnt vmcnt(0)
	v_mul_f32_e32 v23, v9, v160
	s_waitcnt vmcnt(2)
	v_mul_f32_e32 v26, v11, v161
	ds_write2_b32 v22, v23, v26 offset0:8 offset1:74
	s_waitcnt vmcnt(0)
	v_pk_mul_f32 v[20:21], v[18:19], v[162:163]
	s_cbranch_execnz .LBB0_1048

;     ...
;         for (int i = 0; i < 32; ++i) { const int kk = 2 * i + (lane >> 5); tv[i] = W[(size_t)(k0 + kk) * N + n0 + (lane & 31)]; }
; #pragma unroll
;         for (int i = 0; i < 32; ++i) { const int kk = 2 * i + (lane >> 5); float v = tv[i]; if (gk) v *= gk[k0 + kk]; scr[kk * 33 + (lane & 31)] = v; }
.LBB0_1048:
	s_and_b64 vcc, exec, s[2:3]
	v_add_u32_e32 v9, 0x800, v13
	ds_write2_b32 v22, v20, v21 offset0:140 offset1:206
	s_cbranch_vccnz .LBB0_1070
	s_ashr_i32 s7, s6, 31
	v_readlane_b32 s36, v249, 17
	v_lshl_add_u64 v[18:19], s[6:7], 0, v[0:1]
	v_readlane_b32 s48, v249, 29
	v_readlane_b32 s49, v249, 30
	v_readlane_b32 s37, v249, 18
	s_nop 0
	v_lshl_add_u64 v[18:19], v[18:19], 2, s[48:49]
	v_readlane_b32 s38, v249, 19
	v_readlane_b32 s39, v249, 20
	v_readlane_b32 s40, v249, 21
	v_readlane_b32 s41, v249, 22
	v_readlane_b32 s42, v249, 23
	v_readlane_b32 s43, v249, 24
	v_readlane_b32 s44, v249, 25
	v_readlane_b32 s45, v249, 26
	v_readlane_b32 s46, v249, 27
	v_readlane_b32 s47, v249, 28
	v_readlane_b32 s50, v249, 31
	v_readlane_b32 s51, v249, 32
	s_waitcnt vmcnt(0)
	v_mul_f32_e32 v11, v5, v164
	s_waitcnt vmcnt(2)
	v_mul_f32_e32 v13, v7, v165
	ds_write2_b32 v9, v11, v13 offset0:16 offset1:82
	s_waitcnt vmcnt(0)
	v_pk_mul_f32 v[18:19], v[16:17], v[166:167]
	s_cbranch_execnz .LBB0_1051

;     ...
;     for (int item = gw; item < nitems; item += ngw) {
;         const int kb = item / nblk, nb = nb0 + item % nblk, k0 = 64 * kb, n0 = 32 * nb;
;         float tv[32];
; #pragma unroll
;         for (int i = 0; i < 32; ++i) { const int kk = 2 * i + (lane >> 5); tv[i] = W[(size_t)(k0 + kk) * N + n0 + (lane & 31)]; }
; #pragma unroll
;         for (int i = 0; i < 32; ++i) { const int kk = 2 * i + (lane >> 5); float v = tv[i]; if (gk) v *= gk[k0 + kk]; scr[kk * 33 + (lane & 31)] = v; }
; __global__ void __launch_bounds__(512, 2) fwd_mega(Args args) {
;     ...
;             transpose_mat(args.in[28], 1024, 5632, args.in[27], 1, wGU2, nullptr, scr, gw2, ngw2, lane);
.LBB0_1084:
	s_mul_hi_i32 s0, s14, 0x2e8ba2e9
	s_lshr_b32 s1, s0, 31
	s_ashr_i32 s16, s0, 5
	s_add_i32 s16, s16, s1
	s_mul_i32 s15, s16, 0xffffea00
	s_lshl_b32 s0, s16, 6
	s_add_i32 s4, s10, s15
	v_or_b32_e32 v32, s0, v0
	s_ashr_i32 s5, s4, 31
	v_lshl_add_u64 v[16:17], s[4:5], 2, v[14:15]
	v_or_b32_e32 v7, 2, v32
	v_mad_i64_i32 v[20:21], s[6:7], v7, s11, v[16:17]
	v_or_b32_e32 v7, 4, v32
	v_mad_i64_i32 v[22:23], s[6:7], v7, s11, v[16:17]
	v_or_b32_e32 v7, 6, v32
	v_mad_i64_i32 v[24:25], s[6:7], v7, s11, v[16:17]
	v_or_b32_e32 v7, 8, v32
	v_mad_i64_i32 v[26:27], s[6:7], v7, s11, v[16:17]
	v_or_b32_e32 v7, 10, v32
	v_mad_i64_i32 v[28:29], s[6:7], v7, s11, v[16:17]
	v_or_b32_e32 v7, 12, v32
	v_mad_i64_i32 v[48:49], s[6:7], v7, s11, v[16:17]
	v_or_b32_e32 v7, 14, v32
	v_mad_i64_i32 v[18:19], s[6:7], v32, s11, v[16:17]
	v_mad_i64_i32 v[50:51], s[6:7], v7, s11, v[16:17]
	v_or_b32_e32 v7, 16, v32
	global_load_dword v58, v[18:19], off
	global_load_dword v59, v[20:21], off
	global_load_dword v30, v[22:23], off
	global_load_dword v31, v[24:25], off
	global_load_dword v56, v[26:27], off
	global_load_dword v57, v[28:29], off
	s_nop 0
	global_load_dword v28, v[48:49], off
	global_load_dword v29, v[50:51], off
	v_mad_i64_i32 v[18:19], s[6:7], v7, s11, v[16:17]
	v_or_b32_e32 v7, 18, v32
	v_mad_i64_i32 v[20:21], s[6:7], v7, s11, v[16:17]
	v_or_b32_e32 v7, 20, v32
	v_mad_i64_i32 v[22:23], s[6:7], v7, s11, v[16:17]
	v_or_b32_e32 v7, 22, v32
	v_mad_i64_i32 v[24:25], s[6:7], v7, s11, v[16:17]
	v_or_b32_e32 v7, 24, v32
	v_mad_i64_i32 v[48:49], s[6:7], v7, s11, v[16:17]
	v_or_b32_e32 v7, 26, v32
	v_mad_i64_i32 v[50:51], s[6:7], v7, s11, v[16:17]
	v_or_b32_e32 v7, 28, v32
	v_mad_i64_i32 v[60:61], s[6:7], v7, s11, v[16:17]
	v_or_b32_e32 v7, 30, v32
	v_mad_i64_i32 v[62:63], s[6:7], v7, s11, v[16:17]
	v_or_b32_e32 v7, 32, v32
	global_load_dword v54, v[18:19], off
	global_load_dword v55, v[20:21], off
	global_load_dword v26, v[22:23], off
	global_load_dword v27, v[24:25], off
	global_load_dword v52, v[48:49], off
	global_load_dword v53, v[50:51], off
	s_nop 0
	global_load_dword v24, v[60:61], off
	global_load_dword v25, v[62:63], off
	v_mad_i64_i32 v[18:19], s[6:7], v7, s11, v[16:17]
	v_or_b32_e32 v7, 34, v32
	v_mad_i64_i32 v[20:21], s[6:7], v7, s11, v[16:17]
	v_or_b32_e32 v7, 36, v32
	v_mad_i64_i32 v[22:23], s[6:7], v7, s11, v[16:17]
	v_or_b32_e32 v7, 38, v32
	v_mad_i64_i32 v[48:49], s[6:7], v7, s11, v[16:17]
	v_or_b32_e32 v7, 40, v32
	v_mad_i64_i32 v[60:61], s[6:7], v7, s11, v[16:17]
	v_or_b32_e32 v7, 42, v32
	v_mad_i64_i32 v[62:63], s[6:7], v7, s11, v[16:17]
	v_or_b32_e32 v7, 44, v32
	v_mad_i64_i32 v[64:65], s[6:7], v7, s11, v[16:17]
	v_or_b32_e32 v7, 46, v32
	v_mad_i64_i32 v[66:67], s[6:7], v7, s11, v[16:17]
	v_or_b32_e32 v7, 48, v32
	global_load_dword v50, v[18:19], off
	global_load_dword v51, v[20:21], off
	s_nop 0
	global_load_dword v22, v[22:23], off
	s_nop 0
	global_load_dword v23, v[48:49], off
	s_nop 0
	global_load_dword v48, v[60:61], off
	global_load_dword v49, v[62:63], off
	global_load_dword v20, v[64:65], off
	global_load_dword v21, v[66:67], off
	v_mad_i64_i32 v[18:19], s[6:7], v7, s11, v[16:17]
	v_or_b32_e32 v7, 50, v32
	v_mad_i64_i32 v[60:61], s[6:7], v7, s11, v[16:17]
	v_or_b32_e32 v7, 52, v32
	v_mad_i64_i32 v[62:63], s[6:7], v7, s11, v[16:17]
	v_or_b32_e32 v7, 54, v32
	v_mad_i64_i32 v[64:65], s[6:7], v7, s11, v[16:17]
	v_or_b32_e32 v7, 56, v32
	v_mad_i64_i32 v[66:67], s[6:7], v7, s11, v[16:17]
	v_or_b32_e32 v7, 58, v32
	v_mad_i64_i32 v[68:69], s[6:7], v7, s11, v[16:17]
	v_or_b32_e32 v7, 60, v32
	v_mad_i64_i32 v[70:71], s[6:7], v7, s11, v[16:17]
	v_or_b32_e32 v7, 62, v32
	v_mad_i64_i32 v[72:73], s[6:7], v7, s11, v[16:17]
	global_load_dword v11, v[18:19], off
	global_load_dword v13, v[60:61], off
	s_nop 0
	global_load_dword v18, v[62:63], off
	global_load_dword v19, v[64:65], off
	global_load_dword v7, v[66:67], off
	global_load_dword v9, v[68:69], off
	global_load_dword v16, v[70:71], off
	global_load_dword v17, v[72:73], off
	s_and_b64 vcc, exec, s[2:3]
	s_cbranch_vccnz .LBB0_1107
	v_readlane_b32 s36, v249, 1
	v_readlane_b32 s42, v249, 7
	v_readlane_b32 s43, v249, 8
	v_ashrrev_i32_e32 v33, 31, v32
	s_mov_b64 s[22:23], s[42:43]
	s_ashr_i32 s1, s0, 31
	v_lshl_add_u64 v[32:33], v[32:33], 2, s[22:23]
	v_lshl_add_u64 v[60:61], s[0:1], 0, v[0:1]
	v_lshl_add_u64 v[60:61], v[60:61], 2, s[22:23]
	global_load_dword v62, v[32:33], off
	global_load_dword v63, v[60:61], off offset:8
	s_nop 0
	global_load_dword v32, v[60:61], off offset:16
	global_load_dword v33, v[60:61], off offset:24
	global_load_dword v140, v[60:61], off offset:32
	global_load_dword v141, v[60:61], off offset:40
	global_load_dword v142, v[60:61], off offset:48
	global_load_dword v143, v[60:61], off offset:56
	global_load_dword v144, v[60:61], off offset:64
	global_load_dword v145, v[60:61], off offset:72
	global_load_dword v146, v[60:61], off offset:80
	global_load_dword v147, v[60:61], off offset:88
	global_load_dword v148, v[60:61], off offset:96
	global_load_dword v149, v[60:61], off offset:104
	global_load_dword v150, v[60:61], off offset:112
	global_load_dword v151, v[60:61], off offset:120
	global_load_dword v152, v[60:61], off offset:128
	global_load_dword v153, v[60:61], off offset:136
	global_load_dword v154, v[60:61], off offset:144
	global_load_dword v155, v[60:61], off offset:152
	global_load_dword v156, v[60:61], off offset:160
	global_load_dword v157, v[60:61], off offset:168
	global_load_dword v158, v[60:61], off offset:176
	global_load_dword v159, v[60:61], off offset:184
	global_load_dword v160, v[60:61], off offset:192
	global_load_dword v161, v[60:61], off offset:200
	global_load_dword v162, v[60:61], off offset:208
	global_load_dword v163, v[60:61], off offset:216
	global_load_dword v164, v[60:61], off offset:224
	global_load_dword v165, v[60:61], off offset:232
	global_load_dword v166, v[60:61], off offset:240
	global_load_dword v167, v[60:61], off offset:248
	v_readlane_b32 s37, v249, 2
	v_readlane_b32 s38, v249, 3
	v_readlane_b32 s39, v249, 4
	v_readlane_b32 s40, v249, 5
	v_readlane_b32 s41, v249, 6
	v_readlane_b32 s44, v249, 9
	v_readlane_b32 s45, v249, 10
	v_readlane_b32 s46, v249, 11
	v_readlane_b32 s47, v249, 12
	v_readlane_b32 s48, v249, 13
	v_readlane_b32 s49, v249, 14
	v_readlane_b32 s50, v249, 15
	v_readlane_b32 s51, v249, 16
	s_waitcnt vmcnt(0)
	v_mul_f32_e32 v60, v58, v62
	v_mul_f32_e32 v61, v59, v63
	ds_write_b32 v35, v60
	v_pk_mul_f32 v[32:33], v[30:31], v[32:33]
	ds_write_b32 v5, v61
	s_cbranch_execnz .LBB0_1087

;     ...
;         for (int i = 0; i < 32; ++i) { const int kk = 2 * i + (lane >> 5); tv[i] = W[(size_t)(k0 + kk) * N + n0 + (lane & 31)]; }
; #pragma unroll
;         for (int i = 0; i < 32; ++i) { const int kk = 2 * i + (lane >> 5); float v = tv[i]; if (gk) v *= gk[k0 + kk]; scr[kk * 33 + (lane & 31)] = v; }
.LBB0_1087:
	s_and_b64 vcc, exec, s[2:3]
	ds_write2_b32 v46, v32, v33 offset1:66
	s_cbranch_vccnz .LBB0_1108
	s_ashr_i32 s1, s0, 31
	v_readlane_b32 s36, v249, 1
	s_waitcnt vmcnt(0)
	v_lshl_add_u64 v[30:31], s[0:1], 0, v[0:1]
	v_readlane_b32 s42, v249, 7
	v_readlane_b32 s43, v249, 8
	v_readlane_b32 s37, v249, 2
	s_nop 0
	v_lshl_add_u64 v[30:31], v[30:31], 2, s[42:43]
	v_readlane_b32 s38, v249, 3
	v_readlane_b32 s39, v249, 4
	v_readlane_b32 s40, v249, 5
	v_readlane_b32 s41, v249, 6
	v_readlane_b32 s44, v249, 9
	v_readlane_b32 s45, v249, 10
	v_readlane_b32 s46, v249, 11
	v_readlane_b32 s47, v249, 12
	v_readlane_b32 s48, v249, 13
	v_readlane_b32 s49, v249, 14
	v_readlane_b32 s50, v249, 15
	v_readlane_b32 s51, v249, 16
	s_waitcnt vmcnt(0)
	v_mul_f32_e32 v58, v56, v140
	v_mul_f32_e32 v59, v57, v141
	ds_write2_b32 v47, v58, v59 offset1:66
	v_pk_mul_f32 v[30:31], v[28:29], v[142:143]
	s_cbranch_execnz .LBB0_1090

;     ...
;         for (int i = 0; i < 32; ++i) { const int kk = 2 * i + (lane >> 5); tv[i] = W[(size_t)(k0 + kk) * N + n0 + (lane & 31)]; }
; #pragma unroll
;         for (int i = 0; i < 32; ++i) { const int kk = 2 * i + (lane >> 5); float v = tv[i]; if (gk) v *= gk[k0 + kk]; scr[kk * 33 + (lane & 31)] = v; }
.LBB0_1090:
	s_waitcnt vmcnt(0)
	v_add_u32_e32 v28, v37, v38
	ds_write2_b32 v28, v30, v31 offset1:66
	s_and_b64 vcc, exec, s[2:3]
	v_add_u32_e32 v30, v37, v39
	s_cbranch_vccnz .LBB0_1109
	s_ashr_i32 s1, s0, 31
	v_readlane_b32 s36, v249, 1
	v_lshl_add_u64 v[28:29], s[0:1], 0, v[0:1]
	v_readlane_b32 s42, v249, 7
	v_readlane_b32 s43, v249, 8
	v_readlane_b32 s37, v249, 2
	s_nop 0
	v_lshl_add_u64 v[28:29], v[28:29], 2, s[42:43]
	v_readlane_b32 s38, v249, 3
	v_readlane_b32 s39, v249, 4
	v_readlane_b32 s40, v249, 5
	v_readlane_b32 s41, v249, 6
	v_readlane_b32 s44, v249, 9
	v_readlane_b32 s45, v249, 10
	v_readlane_b32 s46, v249, 11
	v_readlane_b32 s47, v249, 12
	v_readlane_b32 s48, v249, 13
	v_readlane_b32 s49, v249, 14
	v_readlane_b32 s50, v249, 15
	v_readlane_b32 s51, v249, 16
	s_waitcnt vmcnt(0)
	v_mul_f32_e32 v31, v54, v144
	v_mul_f32_e32 v56, v55, v145
	ds_write2_b32 v30, v31, v56 offset1:66
	v_pk_mul_f32 v[28:29], v[26:27], v[146:147]
	s_cbranch_execnz .LBB0_1093

;     ...
;         for (int i = 0; i < 32; ++i) { const int kk = 2 * i + (lane >> 5); tv[i] = W[(size_t)(k0 + kk) * N + n0 + (lane & 31)]; }
; #pragma unroll
;         for (int i = 0; i < 32; ++i) { const int kk = 2 * i + (lane >> 5); float v = tv[i]; if (gk) v *= gk[k0 + kk]; scr[kk * 33 + (lane & 31)] = v; }
.LBB0_1093:
	v_add_u32_e32 v26, v37, v40
	ds_write2_b32 v26, v28, v29 offset1:66
	s_and_b64 vcc, exec, s[2:3]
	v_add_u32_e32 v28, v37, v41
	s_cbranch_vccnz .LBB0_1110
	s_ashr_i32 s1, s0, 31
	v_readlane_b32 s36, v249, 1
	v_lshl_add_u64 v[26:27], s[0:1], 0, v[0:1]
	v_readlane_b32 s42, v249, 7
	v_readlane_b32 s43, v249, 8
	v_readlane_b32 s37, v249, 2
	s_nop 0
	v_lshl_add_u64 v[26:27], v[26:27], 2, s[42:43]
	v_readlane_b32 s38, v249, 3
	v_readlane_b32 s39, v249, 4
	v_readlane_b32 s40, v249, 5
	v_readlane_b32 s41, v249, 6
	v_readlane_b32 s44, v249, 9
	v_readlane_b32 s45, v249, 10
	v_readlane_b32 s46, v249, 11
	v_readlane_b32 s47, v249, 12
	v_readlane_b32 s48, v249, 13
	v_readlane_b32 s49, v249, 14
	v_readlane_b32 s50, v249, 15
	v_readlane_b32 s51, v249, 16
	s_waitcnt vmcnt(0)
	v_mul_f32_e32 v29, v52, v148
	v_mul_f32_e32 v32, v53, v149
	ds_write2_b32 v28, v29, v32 offset1:66
	v_pk_mul_f32 v[26:27], v[24:25], v[150:151]
	s_cbranch_execnz .LBB0_1096

;     ...
;         for (int i = 0; i < 32; ++i) { const int kk = 2 * i + (lane >> 5); tv[i] = W[(size_t)(k0 + kk) * N + n0 + (lane & 31)]; }
; #pragma unroll
;         for (int i = 0; i < 32; ++i) { const int kk = 2 * i + (lane >> 5); float v = tv[i]; if (gk) v *= gk[k0 + kk]; scr[kk * 33 + (lane & 31)] = v; }
.LBB0_1096:
	v_add_u32_e32 v24, v37, v42
	ds_write2_b32 v24, v26, v27 offset1:66
	s_and_b64 vcc, exec, s[2:3]
	v_add_u32_e32 v26, v37, v43
	s_cbranch_vccnz .LBB0_1111
	s_ashr_i32 s1, s0, 31
	v_readlane_b32 s36, v249, 1
	v_lshl_add_u64 v[24:25], s[0:1], 0, v[0:1]
	v_readlane_b32 s42, v249, 7
	v_readlane_b32 s43, v249, 8
	v_readlane_b32 s37, v249, 2
	s_nop 0
	v_lshl_add_u64 v[24:25], v[24:25], 2, s[42:43]
	v_readlane_b32 s38, v249, 3
	v_readlane_b32 s39, v249, 4
	v_readlane_b32 s40, v249, 5
	v_readlane_b32 s41, v249, 6
	v_readlane_b32 s44, v249, 9
	v_readlane_b32 s45, v249, 10
	v_readlane_b32 s46, v249, 11
	v_readlane_b32 s47, v249, 12
	v_readlane_b32 s48, v249, 13
	v_readlane_b32 s49, v249, 14
	v_readlane_b32 s50, v249, 15
	v_readlane_b32 s51, v249, 16
	s_waitcnt vmcnt(0)
	v_mul_f32_e32 v27, v50, v152
	v_mul_f32_e32 v30, v51, v153
	ds_write2_b32 v26, v27, v30 offset1:66
	v_pk_mul_f32 v[24:25], v[22:23], v[154:155]
	s_cbranch_execnz .LBB0_1099

;     ...
;         for (int i = 0; i < 32; ++i) { const int kk = 2 * i + (lane >> 5); tv[i] = W[(size_t)(k0 + kk) * N + n0 + (lane & 31)]; }
; #pragma unroll
;         for (int i = 0; i < 32; ++i) { const int kk = 2 * i + (lane >> 5); float v = tv[i]; if (gk) v *= gk[k0 + kk]; scr[kk * 33 + (lane & 31)] = v; }
.LBB0_1099:
	v_add_u32_e32 v22, v37, v44
	ds_write2_b32 v22, v24, v25 offset1:66
	s_and_b64 vcc, exec, s[2:3]
	v_add_u32_e32 v24, v37, v45
	s_cbranch_vccnz .LBB0_1112
	s_ashr_i32 s1, s0, 31
	v_readlane_b32 s36, v249, 1
	v_lshl_add_u64 v[22:23], s[0:1], 0, v[0:1]
	v_readlane_b32 s42, v249, 7
	v_readlane_b32 s43, v249, 8
	v_readlane_b32 s37, v249, 2
	s_nop 0
	v_lshl_add_u64 v[22:23], v[22:23], 2, s[42:43]
	v_readlane_b32 s38, v249, 3
	v_readlane_b32 s39, v249, 4
	v_readlane_b32 s40, v249, 5
	v_readlane_b32 s41, v249, 6
	v_readlane_b32 s44, v249, 9
	v_readlane_b32 s45, v249, 10
	v_readlane_b32 s46, v249, 11
	v_readlane_b32 s47, v249, 12
	v_readlane_b32 s48, v249, 13
	v_readlane_b32 s49, v249, 14
	v_readlane_b32 s50, v249, 15
	v_readlane_b32 s51, v249, 16
	s_waitcnt vmcnt(0)
	v_mul_f32_e32 v25, v48, v156
	v_mul_f32_e32 v28, v49, v157
	ds_write2_b32 v24, v25, v28 offset1:66
	v_pk_mul_f32 v[22:23], v[20:21], v[158:159]
	s_cbranch_execnz .LBB0_1102

;     ...
;         for (int i = 0; i < 32; ++i) { const int kk = 2 * i + (lane >> 5); tv[i] = W[(size_t)(k0 + kk) * N + n0 + (lane & 31)]; }
; #pragma unroll
;         for (int i = 0; i < 32; ++i) { const int kk = 2 * i + (lane >> 5); float v = tv[i]; if (gk) v *= gk[k0 + kk]; scr[kk * 33 + (lane & 31)] = v; }
.LBB0_1102:
	ds_write2_b32 v24, v22, v23 offset0:132 offset1:198
	s_and_b64 vcc, exec, s[2:3]
	v_add_u32_e32 v22, 0x400, v24
	s_cbranch_vccnz .LBB0_1113
	s_ashr_i32 s1, s0, 31
	v_readlane_b32 s36, v249, 1
	v_lshl_add_u64 v[20:21], s[0:1], 0, v[0:1]
	v_readlane_b32 s42, v249, 7
	v_readlane_b32 s43, v249, 8
	v_readlane_b32 s37, v249, 2
	s_nop 0
	v_lshl_add_u64 v[20:21], v[20:21], 2, s[42:43]
	v_readlane_b32 s38, v249, 3
	v_readlane_b32 s39, v249, 4
	v_readlane_b32 s40, v249, 5
	v_readlane_b32 s41, v249, 6
	v_readlane_b32 s44, v249, 9
	v_readlane_b32 s45, v249, 10
	v_readlane_b32 s46, v249, 11
	v_readlane_b32 s47, v249, 12
	v_readlane_b32 s48, v249, 13
	v_readlane_b32 s49, v249, 14
	v_readlane_b32 s50, v249, 15
	v_readlane_b32 s51, v249, 16
	s_waitcnt vmcnt(0)
	v_mul_f32_e32 v23, v11, v160
	v_mul_f32_e32 v25, v13, v161
	ds_write2_b32 v22, v23, v25 offset0:8 offset1:74
	v_pk_mul_f32 v[20:21], v[18:19], v[162:163]
	s_cbranch_execnz .LBB0_1105

;     ...
;         for (int i = 0; i < 32; ++i) { const int kk = 2 * i + (lane >> 5); tv[i] = W[(size_t)(k0 + kk) * N + n0 + (lane & 31)]; }
; #pragma unroll
;         for (int i = 0; i < 32; ++i) { const int kk = 2 * i + (lane >> 5); float v = tv[i]; if (gk) v *= gk[k0 + kk]; scr[kk * 33 + (lane & 31)] = v; }
.LBB0_1105:
	s_and_b64 vcc, exec, s[2:3]
	v_add_u32_e32 v11, 0x800, v24
	ds_write2_b32 v22, v20, v21 offset0:140 offset1:206
	s_cbranch_vccnz .LBB0_1114
	s_ashr_i32 s1, s0, 31
	v_readlane_b32 s36, v249, 1
	v_lshl_add_u64 v[18:19], s[0:1], 0, v[0:1]
	v_readlane_b32 s42, v249, 7
	v_readlane_b32 s43, v249, 8
	v_readlane_b32 s37, v249, 2
	s_nop 0
	v_lshl_add_u64 v[18:19], v[18:19], 2, s[42:43]
	v_readlane_b32 s38, v249, 3
	v_readlane_b32 s39, v249, 4
	v_readlane_b32 s40, v249, 5
	v_readlane_b32 s41, v249, 6
	v_readlane_b32 s44, v249, 9
	v_readlane_b32 s45, v249, 10
	v_readlane_b32 s46, v249, 11
	v_readlane_b32 s47, v249, 12
	v_readlane_b32 s48, v249, 13
	v_readlane_b32 s49, v249, 14
	v_readlane_b32 s50, v249, 15
	v_readlane_b32 s51, v249, 16
	s_waitcnt vmcnt(0)
	v_mul_f32_e32 v13, v7, v164
	v_mul_f32_e32 v22, v9, v165
	ds_write2_b32 v11, v13, v22 offset0:16 offset1:82
	v_pk_mul_f32 v[18:19], v[16:17], v[166:167]
	s_cbranch_execnz .LBB0_1083
	s_branch .LBB0_1115
